# scan loader waves: 98 pairs of scalar v_mul_f32 fused into v_pk_mul_f32 (fewer VALU issues on the SIMDs shared with the recurrence waves)
# baseline (speedup 1.0000x reference)
; #define LAS __attribute__((address_space(3)))
; __device__ __forceinline__ void rwkv_scan(const Params& p, LAS unsigned char* lds, int rowbase, int T, int h, int q4, const float* S0, float* Sout) {
;     ...
;         if (ldr) {
; #pragma unroll
;             for (int q = 0; q < 2; ++q) {
;                 const int st_ = lstep + q * 16;
;                 *(LAS f32x4*)(b + st_ * 256 + lj * 16) = gd[q];
;                 *(LAS f32x4*)(b + 8192 + st_ * 256 + lj * 16) = up4(gk[q]);
;                 *(LAS f32x4*)(b + 16384 + st_ * 256 + lj * 16) = up4(ga[q]);
;                 *(LAS f32x4*)(b + 24576 + st_ * 256 + lj * 16) = up4(gp[q]);
;                 *(LAS f32x4*)(b + 32768 + st_ * 256 + lj * 16) = up4(gr[q]);
;                 if (lj < 4) *(LAS f32x4*)(b + 40960 + st_ * 64 + lj * 16) = up4(gv[q]);
;             }
;         }
;         __syncthreads();
;         if (c + 1 < nch) gload(c + 1);
.Lrw3_lead_done:
.Lrw3_lloop:
	s_waitcnt vmcnt(0)
	v_pk_mul_f32 v[44:45], v[44:45], v[40:41]
	v_pk_mul_f32 v[46:47], v[46:47], v[42:43]
	v_pk_mul_f32 v[48:49], v[48:49], v[44:45]
	v_pk_mul_f32 v[50:51], v[50:51], v[46:47]
	v_pk_mul_f32 v[52:53], v[52:53], v[48:49]
	v_pk_mul_f32 v[54:55], v[54:55], v[50:51]
	v_pk_mul_f32 v[56:57], v[56:57], v[52:53]
	v_pk_mul_f32 v[58:59], v[58:59], v[54:55]
	v_pk_mul_f32 v[60:61], v[60:61], v[56:57]
	v_pk_mul_f32 v[62:63], v[62:63], v[58:59]
	v_pk_mul_f32 v[64:65], v[64:65], v[60:61]
	v_pk_mul_f32 v[66:67], v[66:67], v[62:63]
	v_pk_mul_f32 v[68:69], v[68:69], v[64:65]
	v_pk_mul_f32 v[70:71], v[70:71], v[66:67]
	ds_bpermute_b32 v188, v35, v68
	ds_bpermute_b32 v189, v35, v69
	ds_bpermute_b32 v190, v35, v70
	ds_bpermute_b32 v191, v35, v71
	ds_bpermute_b32 v192, v36, v68
	ds_bpermute_b32 v193, v36, v69
	ds_bpermute_b32 v194, v36, v70
	ds_bpermute_b32 v195, v36, v71
	ds_bpermute_b32 v196, v37, v68
	ds_bpermute_b32 v197, v37, v69
	ds_bpermute_b32 v198, v37, v70
	ds_bpermute_b32 v199, v37, v71
	s_waitcnt lgkmcnt(0)
	v_mov_b32_e32 v2, 1.0
	v_mov_b32_e32 v3, 1.0
	v_mov_b32_e32 v4, 1.0
	v_mov_b32_e32 v5, 1.0
	v_cndmask_b32_e64 v184, v2, v188, s[98:99]
	v_cndmask_b32_e64 v185, v3, v189, s[98:99]
	v_cndmask_b32_e64 v186, v4, v190, s[98:99]
	v_cndmask_b32_e64 v187, v5, v191, s[98:99]
	v_cndmask_b32_e64 v192, v2, v192, s[100:101]
	v_cndmask_b32_e64 v193, v3, v193, s[100:101]
	v_cndmask_b32_e64 v194, v4, v194, s[100:101]
	v_cndmask_b32_e64 v195, v5, v195, s[100:101]
	v_pk_mul_f32 v[184:185], v[184:185], v[192:193]
	v_pk_mul_f32 v[186:187], v[186:187], v[194:195]
	v_cndmask_b32_e64 v196, v2, v196, s[52:53]
	v_cndmask_b32_e64 v197, v3, v197, s[52:53]
	v_cndmask_b32_e64 v198, v4, v198, s[52:53]
	v_cndmask_b32_e64 v199, v5, v199, s[52:53]
	v_pk_mul_f32 v[184:185], v[184:185], v[196:197]
	v_pk_mul_f32 v[186:187], v[186:187], v[198:199]
	v_pk_mul_f32 v[40:41], v[40:41], v[184:185]
	v_pk_mul_f32 v[42:43], v[42:43], v[186:187]
	v_pk_mul_f32 v[44:45], v[44:45], v[184:185]
	v_pk_mul_f32 v[46:47], v[46:47], v[186:187]
	v_pk_mul_f32 v[48:49], v[48:49], v[184:185]
	v_pk_mul_f32 v[50:51], v[50:51], v[186:187]
	v_pk_mul_f32 v[52:53], v[52:53], v[184:185]
	v_pk_mul_f32 v[54:55], v[54:55], v[186:187]
	v_pk_mul_f32 v[56:57], v[56:57], v[184:185]
	v_pk_mul_f32 v[58:59], v[58:59], v[186:187]
	v_pk_mul_f32 v[60:61], v[60:61], v[184:185]
	v_pk_mul_f32 v[62:63], v[62:63], v[186:187]
	v_pk_mul_f32 v[64:65], v[64:65], v[184:185]
	v_pk_mul_f32 v[66:67], v[66:67], v[186:187]
	v_pk_mul_f32 v[68:69], v[68:69], v[184:185]
	v_pk_mul_f32 v[70:71], v[70:71], v[186:187]
	v_rcp_f32_e32 v152, v40
	v_rcp_f32_e32 v153, v41
	v_rcp_f32_e32 v154, v42
	v_rcp_f32_e32 v155, v43
	v_rcp_f32_e32 v156, v44
	v_rcp_f32_e32 v157, v45
	v_rcp_f32_e32 v158, v46
	v_rcp_f32_e32 v159, v47
	v_rcp_f32_e32 v160, v48
	v_rcp_f32_e32 v161, v49
	v_rcp_f32_e32 v162, v50
	v_rcp_f32_e32 v163, v51
	v_rcp_f32_e32 v164, v52
	v_rcp_f32_e32 v165, v53
	v_rcp_f32_e32 v166, v54
	v_rcp_f32_e32 v167, v55
	v_rcp_f32_e32 v168, v56
	v_rcp_f32_e32 v169, v57
	v_rcp_f32_e32 v170, v58
	v_rcp_f32_e32 v171, v59
	v_rcp_f32_e32 v172, v60
	v_rcp_f32_e32 v173, v61
	v_rcp_f32_e32 v174, v62
	v_rcp_f32_e32 v175, v63
	v_rcp_f32_e32 v176, v64
	v_rcp_f32_e32 v177, v65
	v_rcp_f32_e32 v178, v66
	v_rcp_f32_e32 v179, v67
	v_rcp_f32_e32 v180, v68
	v_rcp_f32_e32 v181, v69
	v_rcp_f32_e32 v182, v70
	v_rcp_f32_e32 v183, v71
	s_cmp_lt_u32 s50, 128
	s_cbranch_scc0 .Lrw3_nb3
	s_barrier
.Lrw3_nb3:
	s_add_i32 s50, s50, 1
	v_lshlrev_b32_e32 v6, 16, v72
	v_and_b32_e32 v7, 0xffff0000, v72
	v_lshlrev_b32_e32 v8, 16, v73
	v_and_b32_e32 v9, 0xffff0000, v73
	v_pk_mul_f32 v[202:203], v[6:7], v[184:185]
	v_pk_mul_f32 v[204:205], v[8:9], v[186:187]
	v_lshlrev_b32_e32 v10, 16, v88
	v_and_b32_e32 v11, 0xffff0000, v88
	v_lshlrev_b32_e32 v12, 16, v89
	v_and_b32_e32 v13, 0xffff0000, v89
	v_pk_mul_f32 v[206:207], v[10:11], v[152:153]
	v_pk_mul_f32 v[208:209], v[12:13], v[154:155]
	v_lshlrev_b32_e32 v6, 16, v104
	v_and_b32_e32 v7, 0xffff0000, v104
	v_lshlrev_b32_e32 v8, 16, v105
	v_and_b32_e32 v9, 0xffff0000, v105
	v_pk_mul_f32 v[210:211], v[6:7], v[152:153]
	v_pk_mul_f32 v[212:213], v[8:9], v[154:155]
	v_lshlrev_b32_e32 v10, 16, v120
	v_and_b32_e32 v11, 0xffff0000, v120
	v_lshlrev_b32_e32 v12, 16, v121
	v_and_b32_e32 v13, 0xffff0000, v121
	v_pk_mul_f32 v[214:215], v[10:11], v[40:41]
	v_pk_mul_f32 v[216:217], v[12:13], v[42:43]
	s_sleep 1
	ds_write_b128 v32, v[202:205] offset:0
	ds_write_b128 v32, v[206:209] offset:8192
	ds_write_b128 v32, v[210:213] offset:16384
	ds_write_b128 v32, v[214:217] offset:24576
	v_lshlrev_b32_e32 v6, 16, v74
	v_and_b32_e32 v7, 0xffff0000, v74
	v_lshlrev_b32_e32 v8, 16, v75
	v_and_b32_e32 v9, 0xffff0000, v75
	v_pk_mul_f32 v[218:219], v[6:7], v[40:41]
	v_pk_mul_f32 v[220:221], v[8:9], v[42:43]
	v_lshlrev_b32_e32 v10, 16, v90
	v_and_b32_e32 v11, 0xffff0000, v90
	v_lshlrev_b32_e32 v12, 16, v91
	v_and_b32_e32 v13, 0xffff0000, v91
	v_pk_mul_f32 v[222:223], v[10:11], v[156:157]
	v_pk_mul_f32 v[224:225], v[12:13], v[158:159]
	v_lshlrev_b32_e32 v6, 16, v106
	v_and_b32_e32 v7, 0xffff0000, v106
	v_lshlrev_b32_e32 v8, 16, v107
	v_and_b32_e32 v9, 0xffff0000, v107
	v_pk_mul_f32 v[226:227], v[6:7], v[156:157]
	v_pk_mul_f32 v[228:229], v[8:9], v[158:159]
	v_lshlrev_b32_e32 v10, 16, v122
	v_and_b32_e32 v11, 0xffff0000, v122
	v_lshlrev_b32_e32 v12, 16, v123
	v_and_b32_e32 v13, 0xffff0000, v123
	v_pk_mul_f32 v[230:231], v[10:11], v[44:45]
	v_pk_mul_f32 v[232:233], v[12:13], v[46:47]
	s_sleep 1
	ds_write_b128 v32, v[218:221] offset:256
	ds_write_b128 v32, v[222:225] offset:8448
	ds_write_b128 v32, v[226:229] offset:16640
	ds_write_b128 v32, v[230:233] offset:24832
	s_waitcnt lgkmcnt(4)
; #define LAS __attribute__((address_space(3)))
; __device__ __forceinline__ void rwkv_scan(const Params& p, LAS unsigned char* lds, int rowbase, int T, int h, int q4, const float* S0, float* Sout) {
;     ...
;         if (ldr) {
; #pragma unroll
;             for (int q = 0; q < 2; ++q) {
;                 const int st_ = lstep + q * 16;
;                 *(LAS f32x4*)(b + st_ * 256 + lj * 16) = gd[q];
;                 *(LAS f32x4*)(b + 8192 + st_ * 256 + lj * 16) = up4(gk[q]);
;                 *(LAS f32x4*)(b + 16384 + st_ * 256 + lj * 16) = up4(ga[q]);
;                 *(LAS f32x4*)(b + 24576 + st_ * 256 + lj * 16) = up4(gp[q]);
;                 *(LAS f32x4*)(b + 32768 + st_ * 256 + lj * 16) = up4(gr[q]);
;                 if (lj < 4) *(LAS f32x4*)(b + 40960 + st_ * 64 + lj * 16) = up4(gv[q]);
;             }
;         }
	v_lshlrev_b32_e32 v6, 16, v76
	v_and_b32_e32 v7, 0xffff0000, v76
	v_lshlrev_b32_e32 v8, 16, v77
	v_and_b32_e32 v9, 0xffff0000, v77
	v_pk_mul_f32 v[202:203], v[6:7], v[44:45]
	v_pk_mul_f32 v[204:205], v[8:9], v[46:47]
	v_lshlrev_b32_e32 v10, 16, v92
	v_and_b32_e32 v11, 0xffff0000, v92
	v_lshlrev_b32_e32 v12, 16, v93
	v_and_b32_e32 v13, 0xffff0000, v93
	v_pk_mul_f32 v[206:207], v[10:11], v[160:161]
	v_pk_mul_f32 v[208:209], v[12:13], v[162:163]
	v_lshlrev_b32_e32 v6, 16, v108
	v_and_b32_e32 v7, 0xffff0000, v108
	v_lshlrev_b32_e32 v8, 16, v109
	v_and_b32_e32 v9, 0xffff0000, v109
	v_pk_mul_f32 v[210:211], v[6:7], v[160:161]
	v_pk_mul_f32 v[212:213], v[8:9], v[162:163]
	v_lshlrev_b32_e32 v10, 16, v124
	v_and_b32_e32 v11, 0xffff0000, v124
	v_lshlrev_b32_e32 v12, 16, v125
	v_and_b32_e32 v13, 0xffff0000, v125
	v_pk_mul_f32 v[214:215], v[10:11], v[48:49]
	v_pk_mul_f32 v[216:217], v[12:13], v[50:51]
	s_sleep 1
	ds_write_b128 v32, v[202:205] offset:512
	ds_write_b128 v32, v[206:209] offset:8704
	ds_write_b128 v32, v[210:213] offset:16896
	ds_write_b128 v32, v[214:217] offset:25088
	s_waitcnt lgkmcnt(4)
	v_lshlrev_b32_e32 v6, 16, v78
	v_and_b32_e32 v7, 0xffff0000, v78
	v_lshlrev_b32_e32 v8, 16, v79
	v_and_b32_e32 v9, 0xffff0000, v79
	v_pk_mul_f32 v[218:219], v[6:7], v[48:49]
	v_pk_mul_f32 v[220:221], v[8:9], v[50:51]
	v_lshlrev_b32_e32 v10, 16, v94
	v_and_b32_e32 v11, 0xffff0000, v94
	v_lshlrev_b32_e32 v12, 16, v95
	v_and_b32_e32 v13, 0xffff0000, v95
	v_pk_mul_f32 v[222:223], v[10:11], v[164:165]
	v_pk_mul_f32 v[224:225], v[12:13], v[166:167]
	v_lshlrev_b32_e32 v6, 16, v110
	v_and_b32_e32 v7, 0xffff0000, v110
	v_lshlrev_b32_e32 v8, 16, v111
	v_and_b32_e32 v9, 0xffff0000, v111
	v_pk_mul_f32 v[226:227], v[6:7], v[164:165]
	v_pk_mul_f32 v[228:229], v[8:9], v[166:167]
	v_lshlrev_b32_e32 v10, 16, v126
	v_and_b32_e32 v11, 0xffff0000, v126
	v_lshlrev_b32_e32 v12, 16, v127
	v_and_b32_e32 v13, 0xffff0000, v127
	v_pk_mul_f32 v[230:231], v[10:11], v[52:53]
	v_pk_mul_f32 v[232:233], v[12:13], v[54:55]
	s_sleep 1
	ds_write_b128 v32, v[218:221] offset:768
	ds_write_b128 v32, v[222:225] offset:8960
	ds_write_b128 v32, v[226:229] offset:17152
	ds_write_b128 v32, v[230:233] offset:25344
	s_waitcnt lgkmcnt(4)
	v_lshlrev_b32_e32 v6, 16, v80
	v_and_b32_e32 v7, 0xffff0000, v80
	v_lshlrev_b32_e32 v8, 16, v81
	v_and_b32_e32 v9, 0xffff0000, v81
	v_pk_mul_f32 v[202:203], v[6:7], v[52:53]
	v_pk_mul_f32 v[204:205], v[8:9], v[54:55]
	v_lshlrev_b32_e32 v10, 16, v96
	v_and_b32_e32 v11, 0xffff0000, v96
	v_lshlrev_b32_e32 v12, 16, v97
	v_and_b32_e32 v13, 0xffff0000, v97
	v_pk_mul_f32 v[206:207], v[10:11], v[168:169]
	v_pk_mul_f32 v[208:209], v[12:13], v[170:171]
	v_lshlrev_b32_e32 v6, 16, v112
	v_and_b32_e32 v7, 0xffff0000, v112
	v_lshlrev_b32_e32 v8, 16, v113
	v_and_b32_e32 v9, 0xffff0000, v113
	v_pk_mul_f32 v[210:211], v[6:7], v[168:169]
	v_pk_mul_f32 v[212:213], v[8:9], v[170:171]
	v_lshlrev_b32_e32 v10, 16, v128
	v_and_b32_e32 v11, 0xffff0000, v128
	v_lshlrev_b32_e32 v12, 16, v129
	v_and_b32_e32 v13, 0xffff0000, v129
	v_pk_mul_f32 v[214:215], v[10:11], v[56:57]
	v_pk_mul_f32 v[216:217], v[12:13], v[58:59]
	s_sleep 1
	ds_write_b128 v32, v[202:205] offset:1024
	ds_write_b128 v32, v[206:209] offset:9216
	ds_write_b128 v32, v[210:213] offset:17408
	ds_write_b128 v32, v[214:217] offset:25600
	s_waitcnt lgkmcnt(4)
	v_lshlrev_b32_e32 v6, 16, v82
	v_and_b32_e32 v7, 0xffff0000, v82
	v_lshlrev_b32_e32 v8, 16, v83
	v_and_b32_e32 v9, 0xffff0000, v83
	v_pk_mul_f32 v[218:219], v[6:7], v[56:57]
	v_pk_mul_f32 v[220:221], v[8:9], v[58:59]
	v_lshlrev_b32_e32 v10, 16, v98
	v_and_b32_e32 v11, 0xffff0000, v98
	v_lshlrev_b32_e32 v12, 16, v99
	v_and_b32_e32 v13, 0xffff0000, v99
	v_pk_mul_f32 v[222:223], v[10:11], v[172:173]
	v_pk_mul_f32 v[224:225], v[12:13], v[174:175]
	v_lshlrev_b32_e32 v6, 16, v114
	v_and_b32_e32 v7, 0xffff0000, v114
	v_lshlrev_b32_e32 v8, 16, v115
	v_and_b32_e32 v9, 0xffff0000, v115
	v_pk_mul_f32 v[226:227], v[6:7], v[172:173]
	v_pk_mul_f32 v[228:229], v[8:9], v[174:175]
	v_lshlrev_b32_e32 v10, 16, v130
	v_and_b32_e32 v11, 0xffff0000, v130
	v_lshlrev_b32_e32 v12, 16, v131
	v_and_b32_e32 v13, 0xffff0000, v131
	v_pk_mul_f32 v[230:231], v[10:11], v[60:61]
	v_pk_mul_f32 v[232:233], v[12:13], v[62:63]
	s_sleep 1
	ds_write_b128 v32, v[218:221] offset:1280
	ds_write_b128 v32, v[222:225] offset:9472
	ds_write_b128 v32, v[226:229] offset:17664
	ds_write_b128 v32, v[230:233] offset:25856
	s_waitcnt lgkmcnt(4)
; #define LAS __attribute__((address_space(3)))
; __device__ __forceinline__ void rwkv_scan(const Params& p, LAS unsigned char* lds, int rowbase, int T, int h, int q4, const float* S0, float* Sout) {
;     ...
;         if (ldr) {
; #pragma unroll
;             for (int q = 0; q < 2; ++q) {
;                 const int st_ = lstep + q * 16;
;                 *(LAS f32x4*)(b + st_ * 256 + lj * 16) = gd[q];
;                 *(LAS f32x4*)(b + 8192 + st_ * 256 + lj * 16) = up4(gk[q]);
;                 *(LAS f32x4*)(b + 16384 + st_ * 256 + lj * 16) = up4(ga[q]);
;                 *(LAS f32x4*)(b + 24576 + st_ * 256 + lj * 16) = up4(gp[q]);
;                 *(LAS f32x4*)(b + 32768 + st_ * 256 + lj * 16) = up4(gr[q]);
;                 if (lj < 4) *(LAS f32x4*)(b + 40960 + st_ * 64 + lj * 16) = up4(gv[q]);
;             }
;         }
;         __syncthreads();
;         if (c + 1 < nch) gload(c + 1);
	v_lshlrev_b32_e32 v6, 16, v84
	v_and_b32_e32 v7, 0xffff0000, v84
	v_lshlrev_b32_e32 v8, 16, v85
	v_and_b32_e32 v9, 0xffff0000, v85
	v_pk_mul_f32 v[202:203], v[6:7], v[60:61]
	v_pk_mul_f32 v[204:205], v[8:9], v[62:63]
	v_lshlrev_b32_e32 v10, 16, v100
	v_and_b32_e32 v11, 0xffff0000, v100
	v_lshlrev_b32_e32 v12, 16, v101
	v_and_b32_e32 v13, 0xffff0000, v101
	v_pk_mul_f32 v[206:207], v[10:11], v[176:177]
	v_pk_mul_f32 v[208:209], v[12:13], v[178:179]
	v_lshlrev_b32_e32 v6, 16, v116
	v_and_b32_e32 v7, 0xffff0000, v116
	v_lshlrev_b32_e32 v8, 16, v117
	v_and_b32_e32 v9, 0xffff0000, v117
	v_pk_mul_f32 v[210:211], v[6:7], v[176:177]
	v_pk_mul_f32 v[212:213], v[8:9], v[178:179]
	v_lshlrev_b32_e32 v10, 16, v132
	v_and_b32_e32 v11, 0xffff0000, v132
	v_lshlrev_b32_e32 v12, 16, v133
	v_and_b32_e32 v13, 0xffff0000, v133
	v_pk_mul_f32 v[214:215], v[10:11], v[64:65]
	v_pk_mul_f32 v[216:217], v[12:13], v[66:67]
	s_sleep 1
	ds_write_b128 v32, v[202:205] offset:1536
	ds_write_b128 v32, v[206:209] offset:9728
	ds_write_b128 v32, v[210:213] offset:17920
	ds_write_b128 v32, v[214:217] offset:26112
	s_waitcnt lgkmcnt(4)
	v_lshlrev_b32_e32 v6, 16, v86
	v_and_b32_e32 v7, 0xffff0000, v86
	v_lshlrev_b32_e32 v8, 16, v87
	v_and_b32_e32 v9, 0xffff0000, v87
	v_pk_mul_f32 v[218:219], v[6:7], v[64:65]
	v_pk_mul_f32 v[220:221], v[8:9], v[66:67]
	v_lshlrev_b32_e32 v10, 16, v102
	v_and_b32_e32 v11, 0xffff0000, v102
	v_lshlrev_b32_e32 v12, 16, v103
	v_and_b32_e32 v13, 0xffff0000, v103
	v_pk_mul_f32 v[222:223], v[10:11], v[180:181]
	v_pk_mul_f32 v[224:225], v[12:13], v[182:183]
	v_lshlrev_b32_e32 v6, 16, v118
	v_and_b32_e32 v7, 0xffff0000, v118
	v_lshlrev_b32_e32 v8, 16, v119
	v_and_b32_e32 v9, 0xffff0000, v119
	v_pk_mul_f32 v[226:227], v[6:7], v[180:181]
	v_pk_mul_f32 v[228:229], v[8:9], v[182:183]
	v_lshlrev_b32_e32 v10, 16, v134
	v_and_b32_e32 v11, 0xffff0000, v134
	v_lshlrev_b32_e32 v12, 16, v135
	v_and_b32_e32 v13, 0xffff0000, v135
	v_pk_mul_f32 v[230:231], v[10:11], v[68:69]
	v_pk_mul_f32 v[232:233], v[12:13], v[70:71]
	s_sleep 1
	ds_write_b128 v32, v[218:221] offset:1792
	ds_write_b128 v32, v[222:225] offset:9984
	ds_write_b128 v32, v[226:229] offset:18176
	ds_write_b128 v32, v[230:233] offset:26368
	s_mov_b64 exec, s[52:53]
	ds_write_b128 v34, v[68:71]
	s_mov_b64 exec, -1
	s_waitcnt lgkmcnt(0)
	v_lshlrev_b32_e32 v202, 16, v136
	v_and_b32_e32 v210, 0xffff0000, v136
	v_lshlrev_b32_e32 v218, 16, v137
	v_and_b32_e32 v226, 0xffff0000, v137
	v_lshlrev_b32_e32 v203, 16, v138
	v_and_b32_e32 v211, 0xffff0000, v138
	v_lshlrev_b32_e32 v219, 16, v139
	v_and_b32_e32 v227, 0xffff0000, v139
	v_lshlrev_b32_e32 v204, 16, v140
	v_and_b32_e32 v212, 0xffff0000, v140
	v_lshlrev_b32_e32 v220, 16, v141
	v_and_b32_e32 v228, 0xffff0000, v141
	v_lshlrev_b32_e32 v205, 16, v142
	v_and_b32_e32 v213, 0xffff0000, v142
	v_lshlrev_b32_e32 v221, 16, v143
	v_and_b32_e32 v229, 0xffff0000, v143
	v_lshlrev_b32_e32 v206, 16, v144
	v_and_b32_e32 v214, 0xffff0000, v144
	v_lshlrev_b32_e32 v222, 16, v145
	v_and_b32_e32 v230, 0xffff0000, v145
	v_lshlrev_b32_e32 v207, 16, v146
	v_and_b32_e32 v215, 0xffff0000, v146
	v_lshlrev_b32_e32 v223, 16, v147
	v_and_b32_e32 v231, 0xffff0000, v147
	v_lshlrev_b32_e32 v208, 16, v148
	v_and_b32_e32 v216, 0xffff0000, v148
	v_lshlrev_b32_e32 v224, 16, v149
	v_and_b32_e32 v232, 0xffff0000, v149
	v_lshlrev_b32_e32 v209, 16, v150
	v_and_b32_e32 v217, 0xffff0000, v150
	v_lshlrev_b32_e32 v225, 16, v151
	v_and_b32_e32 v233, 0xffff0000, v151
	s_mov_b64 exec, s[30:31]
	ds_write_b128 v33, v[202:205] offset:0
	ds_write_b128 v33, v[206:209] offset:16
	ds_write_b128 v33, v[210:213] offset:144
	ds_write_b128 v33, v[214:217] offset:160
	ds_write_b128 v33, v[218:221] offset:288
	ds_write_b128 v33, v[222:225] offset:304
	ds_write_b128 v33, v[226:229] offset:432
	ds_write_b128 v33, v[230:233] offset:448
	s_mov_b64 exec, -1
	s_waitcnt lgkmcnt(0)
	s_cmp_lt_u32 s50, 128
	s_cbranch_scc0 .Lrw3_nb4
	s_barrier
